# dil mixer unit-end stores: eight 16-byte-strided global_store_dwordx2 widened to four dwordx4 with v_permlane32_swap_b32 pairs (upper half-wave +8 B); the unit-seam vmcnt waits lowered by the four rem
# baseline (speedup 1.0000x reference)
; #define MFMA32(a, b, c) __builtin_amdgcn_mfma_f32_32x32x16_bf16((a), (b), (c), 0, 0, 0)
; DI void mix_dil(WVP u16* __restrict__ proj, float* __restrict__ lse, const float* __restrict__ rel_bias, char* smem) {
;     ...
;   for (int u = u_first; u < u_end; u += u_step) {
;     long tbase; int q0, H, dil, j0; DIL_DECODE(u, tbase, q0, H, dil, j0)
;     u16* qp = proj + (tbase + (long)(q0 + l31) * dil) * INW + O1 + H * 64;
;     bf16x8 bq[4];
;     for (int s = 0; s < 4; ++s) bq[s] = bq_n[s];
;     f32x16 O[2]; for (int e = 0; e < 2; ++e) for (int i = 0; i < 16; ++i) O[e][i] = 0.f;
;     float mrun = -1e30f, lsum = 0.f;
;     const float* bt = btab + H * 132;
;     const u16* kbase_ = proj + tbase * INW + O1 + 768 + H * 64;
;     f32x16 sacc; for (int i = 0; i < 16; ++i) sacc[i] = 0.f;
;     for (int s = 0; s < 4; ++s) sacc = MFMA32(ak_n[s], bq[s], sacc);
;     u32x4 vv[4];
;     for (int c = 0; c < 4; ++c) vv[c] = vv_n[c];
.LBB0_337:
	s_or_b64 exec, exec, s[12:13]
	s_waitcnt vmcnt(6)
	v_mov_b64_e32 v[130:131], v[114:115]
	s_waitcnt vmcnt(5)
	v_mov_b64_e32 v[134:135], v[118:119]
	s_waitcnt vmcnt(4)
	v_mov_b64_e32 v[142:143], v[126:127]
	v_mov_b64_e32 v[138:139], v[122:123]
	v_mov_b64_e32 v[96:97], v[144:145]
	v_mov_b64_e32 v[100:101], v[148:149]
	v_mov_b64_e32 v[104:105], v[152:153]
	v_mov_b64_e32 v[108:109], v[156:157]
	s_cmpk_lt_i32 s4, 0x3000
	v_mov_b64_e32 v[128:129], v[112:113]
	v_mov_b64_e32 v[132:133], v[116:117]
	v_mov_b64_e32 v[140:141], v[124:125]
	v_mov_b64_e32 v[136:137], v[120:121]
	v_mov_b64_e32 v[98:99], v[146:147]
	v_mov_b64_e32 v[102:103], v[150:151]
	v_mov_b64_e32 v[106:107], v[154:155]
	v_mov_b64_e32 v[110:111], v[158:159]
	s_cbranch_scc0 .LBB0_351

; DI void store4bf(u16* p, f32x4 a) { uint2 v; v.x = pack2(a[0], a[1]); v.y = pack2(a[2], a[3]); *(uint2*)p = v; }
; DI float flog2(float x) { return __builtin_amdgcn_logf(x); }
; DI float shflx(float v, int mask, int lane) { return __int_as_float(__builtin_amdgcn_ds_bpermute((lane ^ mask) << 2, __float_as_int(v))); }
; DI void mix_dil(WVP u16* __restrict__ proj, float* __restrict__ lse, const float* __restrict__ rel_bias, char* smem) {
;     ...
;     float ltot = lsum + shflx(lsum, 32, lane);
;     float inv = 1.f / ltot;
;     for (int e = 0; e < 2; ++e) for (int gq = 0; gq < 4; ++gq) {
;       f32x4 o4 = {O[e][4 * gq] * inv, O[e][4 * gq + 1] * inv, O[e][4 * gq + 2] * inv, O[e][4 * gq + 3] * inv};
;       store4bf(qp + 32 * e + 8 * gq + 4 * h, o4);
;     }
;     if (h == 0) lse[(tbase + (long)(q0 + l31) * dil) * 12 + H] = (mrun + flog2(ltot)) * 0.6931471805599453f;
.LBB0_349:
	v_or_b32_e32 v0, s1, v206
	v_lshlrev_b64 v[2:3], s0, v[0:1]
	ds_bpermute_b32 v0, v208, v5
	v_lshl_add_u64 v[2:3], v[2:3], 0, s[14:15]
	v_mov_b64_e32 v[6:7], s[54:55]
	v_mad_u64_u32 v[6:7], s[0:1], v2, s86, v[6:7]
	s_waitcnt lgkmcnt(0)
	v_add_f32_e32 v0, v5, v0
	v_div_scale_f32 v5, s[0:1], v0, v0, 1.0
	v_rcp_f32_e32 v10, v5
	v_mov_b32_e32 v8, v7
	v_mad_u64_u32 v[8:9], s[0:1], v3, s86, v[8:9]
	v_mov_b32_e32 v7, v8
	v_fma_f32 v8, -v5, v10, 1.0
	v_fmac_f32_e32 v10, v8, v10
	v_div_scale_f32 v8, vcc, 1.0, v0, 1.0
	v_mul_f32_e32 v9, v8, v10
	v_fma_f32 v11, -v5, v9, v8
	v_fmac_f32_e32 v9, v11, v10
	v_fma_f32 v5, -v5, v9, v8
	v_div_fmas_f32 v5, v5, v10, v9
	v_div_fixup_f32 v8, v5, v0, 1.0
	v_lshl_add_u64 v[6:7], s[12:13], 1, v[6:7]
	v_mov_b32_e32 v185, v1
	v_lshl_add_u64 v[6:7], v[6:7], 0, v[184:185]
	v_mbcnt_lo_u32_b32 v12, -1, 0
	v_mbcnt_hi_u32_b32 v12, -1, v12
	v_and_b32_e32 v12, 32, v12
	v_lshrrev_b32_e32 v12, 2, v12
	v_mov_b32_e32 v13, 0
	v_lshl_add_u64 v[6:7], v[6:7], 0, v[12:13]
	v_pk_mul_f32 v[10:11], v[32:33], v[8:9] op_sel_hi:[1,0]
	v_pk_mul_f32 v[32:33], v[34:35], v[8:9] op_sel_hi:[1,0]
	v_pk_mul_f32 v[12:13], v[36:37], v[8:9] op_sel_hi:[1,0]
	v_pk_mul_f32 v[36:37], v[38:39], v[8:9] op_sel_hi:[1,0]
	v_cvt_pk_bf16_f32 v10, v10, v11
	v_cvt_pk_bf16_f32 v11, v32, v33
	v_cvt_pk_bf16_f32 v12, v12, v13
	v_cvt_pk_bf16_f32 v13, v36, v37
	s_nop 1
	v_permlane32_swap_b32 v10, v12
	v_permlane32_swap_b32 v11, v13
	global_store_dwordx4 v[6:7], v[10:13], off offset:1024
	s_nop 1
	v_pk_mul_f32 v[10:11], v[40:41], v[8:9] op_sel_hi:[1,0]
	v_pk_mul_f32 v[40:41], v[42:43], v[8:9] op_sel_hi:[1,0]
	v_pk_mul_f32 v[12:13], v[44:45], v[8:9] op_sel_hi:[1,0]
	v_pk_mul_f32 v[44:45], v[46:47], v[8:9] op_sel_hi:[1,0]
	v_cvt_pk_bf16_f32 v10, v10, v11
	v_cvt_pk_bf16_f32 v11, v40, v41
	v_cvt_pk_bf16_f32 v12, v12, v13
	v_cvt_pk_bf16_f32 v13, v44, v45
	s_nop 1
	v_permlane32_swap_b32 v10, v12
	v_permlane32_swap_b32 v11, v13
	global_store_dwordx4 v[6:7], v[10:13], off offset:1056
	s_nop 1
	v_pk_mul_f32 v[10:11], v[16:17], v[8:9] op_sel_hi:[1,0]
	v_pk_mul_f32 v[16:17], v[18:19], v[8:9] op_sel_hi:[1,0]
	v_pk_mul_f32 v[12:13], v[20:21], v[8:9] op_sel_hi:[1,0]
	v_pk_mul_f32 v[20:21], v[22:23], v[8:9] op_sel_hi:[1,0]
	v_cvt_pk_bf16_f32 v10, v10, v11
	v_cvt_pk_bf16_f32 v11, v16, v17
	v_cvt_pk_bf16_f32 v12, v12, v13
	v_cvt_pk_bf16_f32 v13, v20, v21
	s_nop 1
	v_permlane32_swap_b32 v10, v12
	v_permlane32_swap_b32 v11, v13
	global_store_dwordx4 v[6:7], v[10:13], off offset:1088
	s_nop 1
	v_pk_mul_f32 v[10:11], v[24:25], v[8:9] op_sel_hi:[1,0]
	v_pk_mul_f32 v[24:25], v[26:27], v[8:9] op_sel_hi:[1,0]
	v_pk_mul_f32 v[12:13], v[28:29], v[8:9] op_sel_hi:[1,0]
	v_pk_mul_f32 v[28:29], v[30:31], v[8:9] op_sel_hi:[1,0]
	v_cvt_pk_bf16_f32 v10, v10, v11
	v_cvt_pk_bf16_f32 v11, v24, v25
	v_cvt_pk_bf16_f32 v12, v12, v13
	v_cvt_pk_bf16_f32 v13, v28, v29
	s_nop 1
	v_permlane32_swap_b32 v10, v12
	v_permlane32_swap_b32 v11, v13
	global_store_dwordx4 v[6:7], v[10:13], off offset:1120
	s_nop 1
	s_and_saveexec_b64 s[12:13], s[8:9]
	s_cbranch_execz .LBB0_337
	v_log_f32_e32 v0, v0
	v_readlane_b32 s0, v255, 45
	v_readlane_b32 s1, v255, 46
	s_ashr_i32 s11, s10, 31
	v_add_f32_e32 v0, v4, v0
	v_mad_u64_u32 v[6:7], s[0:1], v2, 48, s[0:1]
	v_mul_f32_e32 v4, 0x3f317218, v0
	v_mov_b32_e32 v0, v7
	v_mad_u64_u32 v[2:3], s[0:1], v3, 48, v[0:1]
	v_mov_b32_e32 v7, v2
	v_lshl_add_u64 v[2:3], s[10:11], 2, v[6:7]
	global_store_dword v[2:3], v4, off
	s_branch .LBB0_337
